# combo10 = combo9 + full barriers: leaders arrive with a non-returning add and everyone polls the monotonic cross-XCD arrival counter (no returning atomic, no release-word hop)
# baseline (speedup 1.0000x reference)
; __device__ __forceinline__ unsigned xb_ld(unsigned* p)              { return __hip_atomic_load(p, __ATOMIC_RELAXED, __HIP_MEMORY_SCOPE_AGENT); }
; #define XB_SPIN(cond, bar) do { unsigned _sp = 0; while (cond) { __builtin_amdgcn_s_sleep(1); \
;     if ((++_sp & 255u) == 0u) { if (xb_ld(&(bar)[XB_TMO])) break; if (_sp > XB_SPIN_CAP) { atomicAdd(&(bar)[XB_TMO], 1u); break; } } } } while (0)
; __device__ __forceinline__ void xcd_barrier(const XcdBarrier& b) {
;     ...
;         } else {
;             XB_SPIN(xb_ld(&bar[XB_XGEN(b.x)]) == gen, bar);
.Lnl_full:
	s_add_u32 s10, s78, 0x3400
	s_addc_u32 s11, s79, 0
	s_add_i32 s99, s101, 1
	v_mul_lo_u32 v1, v0, s99
	v_add_u32_e32 v1, -1, v1

; __device__ __forceinline__ unsigned xb_ld(unsigned* p)              { return __hip_atomic_load(p, __ATOMIC_RELAXED, __HIP_MEMORY_SCOPE_AGENT); }
; __device__ __forceinline__ unsigned xb_add(unsigned* p, unsigned v) { return __hip_atomic_fetch_add(p, v, __ATOMIC_RELAXED, __HIP_MEMORY_SCOPE_AGENT); }
; #define XB_SPIN(cond, bar) do { unsigned _sp = 0; while (cond) { __builtin_amdgcn_s_sleep(1); \
;     if ((++_sp & 255u) == 0u) { if (xb_ld(&(bar)[XB_TMO])) break; if (_sp > XB_SPIN_CAP) { atomicAdd(&(bar)[XB_TMO], 1u); break; } } } } while (0)
; __device__ __forceinline__ void xcd_barrier(const XcdBarrier& b) {
;     ...
;         if (old + 1u == (gen + 1u) * nloc) {
;             __builtin_amdgcn_fence(__ATOMIC_RELEASE, "agent");
;             asm volatile("s_waitcnt vmcnt(0)" ::: "memory");
;             const unsigned og = xb_add(&bar[XB_TOP], 1u);
;             const unsigned tg = og / nx;
;             if (og + 1u == (tg + 1u) * nx) xb_add(&bar[XB_TOPGEN], 1u);
;             else XB_SPIN(xb_ld(&bar[XB_TOPGEN]) == tg, bar);
;             __builtin_amdgcn_fence(__ATOMIC_ACQUIRE, "agent");
;             xb_add(&bar[XB_XGEN(b.x)], 1u);
;             asm volatile("s_waitcnt vmcnt(0)" ::: "memory");
.Lbar_full:
	buffer_wbl2 sc1
	s_waitcnt lgkmcnt(0)
	s_waitcnt vmcnt(0)
	v_mov_b32_e32 v1, 0x3000
	global_atomic_add v1, v233, s[78:79] offset:1024
	s_add_i32 s99, s101, 1
	v_mul_lo_u32 v1, v0, s99
	v_add_u32_e32 v1, -1, v1
	s_add_u32 s10, s78, 0x3400
	s_addc_u32 s11, s79, 0
	s_mov_b32 s99, 0
.Lld_spin:
	global_load_dword v0, v129, s[10:11] sc1
	s_waitcnt vmcnt(0)
	v_cmp_gt_u32_e32 vcc, v0, v1
	s_cbranch_vccnz .Lld_done
	s_add_i32 s99, s99, 1
	s_cmp_gt_u32 s99, 0x100000
	s_cbranch_scc1 .Lld_done
	s_sleep 1
	s_branch .Lld_spin
.Lld_done:
	s_branch .Lbar_local
	v_cvt_f32_u32_e32 v2, v0
	v_sub_u32_e32 v3, 0, v0
	s_add_u32 s6, s78, 0x3500
	s_addc_u32 s7, s79, 0
	v_rcp_iflag_f32_e32 v2, v2
	s_mov_b64 s[10:11], -1
	v_mul_f32_e32 v2, 0x4f7ffffe, v2
	v_cvt_u32_f32_e32 v2, v2
	v_mul_lo_u32 v3, v3, v2
	v_mul_hi_u32 v3, v2, v3
	v_add_u32_e32 v2, v2, v3
	s_waitcnt vmcnt(0)
	v_mul_hi_u32 v2, v1, v2
	v_mul_lo_u32 v3, v2, v0
	v_sub_u32_e32 v3, v1, v3
	v_cmp_ge_u32_e32 vcc, v3, v0
	v_add_u32_e32 v4, 1, v2
	v_add_u32_e32 v1, 1, v1
	v_cndmask_b32_e32 v2, v2, v4, vcc
	v_sub_u32_e32 v4, v3, v0
	v_cndmask_b32_e32 v3, v3, v4, vcc
	v_cmp_ge_u32_e32 vcc, v3, v0
	v_add_u32_e32 v3, 1, v2
	s_nop 0
	v_cndmask_b32_e32 v2, v2, v3, vcc
	v_mul_lo_u32 v3, v0, v2
	v_add_u32_e32 v0, v3, v0
	v_cmp_ne_u32_e32 vcc, v1, v0
	v_mov_b64_e32 v[0:1], s[6:7]
	s_and_saveexec_b64 s[8:9], vcc
	s_cbranch_execz .LBB0_711
	global_load_dword v0, v129, s[6:7] sc1
	s_mov_b64 s[28:29], 0
	s_waitcnt vmcnt(0)
	v_cmp_eq_u32_e32 vcc, v0, v2
	s_and_saveexec_b64 s[12:13], vcc
	s_cbranch_execz .LBB0_710
	s_add_u32 s10, s78, 0x200
	s_addc_u32 s11, s79, 0
	s_mov_b32 s15, 1
	s_branch .LBB0_703
